# k16 + one static s_setprio 1 for waves 4-7 during the L0 attention and MLA attention phases (reset to 0 at phase end)
# speedup vs baseline: 1.0114x; 1.0114x over previous
; __global__ void __launch_bounds__(512, 2) fwd_kernel(Params P) {
;     ...
;                     { const bf16_t* QK = (const bf16_t*)(ws + WS_QK0); const bf16_t* VT = (const bf16_t*)(ws + WS_VT0);
;                       float la = IN(11)[lane] * IN(12)[lane], lb2 = IN(13)[lane] * IN(14)[lane];
;                       la = wave_sum(la); lb2 = wave_sum(lb2);
;                       const float lam = expf(la) - expf(lb2) + 0.2f;
.LBB0_563:
	v_readlane_b32 s0, v254, 8
	s_cmp_lt_i32 s0, 5
	s_cselect_b64 s[38:39], -1, 0
	s_and_b64 s[0:1], s[38:39], s[6:7]
	s_andn2_b64 vcc, exec, s[0:1]
	s_cbranch_vccnz .LBB0_638
	v_readlane_b32 s98, v254, 7
	s_nop 3
	s_cmp_lt_u32 s98, 4
	s_cbranch_scc1 .Lk16_prio_l0
	s_setprio 1
.Lk16_prio_l0:
	v_mbcnt_lo_u32_b32 v0, -1, 0
	v_mbcnt_hi_u32_b32 v0, -1, v0
	s_mov_b32 s84, 0
	s_ashr_i32 s85, s84, 31
	s_add_u32 s0, s94, s84
	s_addc_u32 s1, s95, s85
	s_add_u32 s37, s0, 0xaa00000
	s_addc_u32 s40, s1, 0
	v_writelane_b32 v254, s0, 13
	s_add_u32 s41, s0, 0x12a00000
	v_writelane_b32 v254, s1, 14
	s_addc_u32 s42, s1, 0
	s_lshl_b64 s[0:1], s[84:85], 3
	v_readlane_b32 s2, v254, 5
	v_readlane_b32 s3, v254, 6
	s_add_u32 s6, s2, s0
	s_addc_u32 s7, s3, s1
	s_load_dwordx8 s[8:15], s[6:7], 0x58
	v_and_b32_e32 v0, 63, v0
	v_lshlrev_b32_e32 v0, 2, v0
	s_waitcnt lgkmcnt(0)
	global_load_dword v1, v0, s[8:9]
	global_load_dword v2, v0, s[10:11]
	global_load_dword v3, v0, s[12:13]
	global_load_dword v4, v0, s[14:15]
	v_mbcnt_lo_u32_b32 v0, -1, 0
	v_mbcnt_hi_u32_b32 v0, -1, v0
	v_and_b32_e32 v5, 64, v0
	v_xor_b32_e32 v6, 1, v0
	v_add_u32_e32 v5, 64, v5
	v_cmp_lt_i32_e32 vcc, v6, v5
	v_xor_b32_e32 v7, 2, v0
	v_xor_b32_e32 v8, 4, v0
	v_cndmask_b32_e32 v6, v0, v6, vcc
	v_lshlrev_b32_e32 v6, 2, v6
	v_cmp_lt_i32_e32 vcc, v7, v5
	v_xor_b32_e32 v9, 8, v0
	v_xor_b32_e32 v10, 16, v0
	v_cndmask_b32_e32 v7, v0, v7, vcc
	v_lshlrev_b32_e32 v7, 2, v7
	v_cmp_lt_i32_e32 vcc, v8, v5
	v_xor_b32_e32 v11, 32, v0
	s_not_b32 s0, s88
	s_add_i32 s43, s80, s0
	v_readlane_b32 s0, v254, 0
	s_and_b32 s44, s0, 0xffffffc0
	v_readlane_b32 s0, v254, 7
	s_lshl_b32 s45, s0, 5
	s_cmpk_lt_i32 s88, 0x200
	s_mov_b32 s0, 0
	s_waitcnt vmcnt(0)
	v_mul_f32_e32 v12, v1, v2
	ds_bpermute_b32 v12, v6, v12
	v_mul_f32_e32 v13, v3, v4
	ds_bpermute_b32 v6, v6, v13
	s_waitcnt lgkmcnt(1)
	v_fmac_f32_e32 v12, v1, v2
	ds_bpermute_b32 v1, v7, v12
	s_waitcnt lgkmcnt(1)
	v_fmac_f32_e32 v6, v3, v4
	ds_bpermute_b32 v2, v7, v6
	v_cndmask_b32_e32 v3, v0, v8, vcc
	v_lshlrev_b32_e32 v3, 2, v3
	s_waitcnt lgkmcnt(1)
	v_add_f32_e32 v1, v12, v1
	ds_bpermute_b32 v4, v3, v1
	s_waitcnt lgkmcnt(1)
	v_add_f32_e32 v2, v6, v2
	ds_bpermute_b32 v3, v3, v2
	v_cmp_lt_i32_e32 vcc, v9, v5
	s_waitcnt lgkmcnt(1)
	v_add_f32_e32 v1, v1, v4
	v_cndmask_b32_e32 v6, v0, v9, vcc
	v_lshlrev_b32_e32 v6, 2, v6
	s_waitcnt lgkmcnt(0)
	v_add_f32_e32 v2, v2, v3
	ds_bpermute_b32 v3, v6, v1
	ds_bpermute_b32 v4, v6, v2
	v_cmp_lt_i32_e32 vcc, v10, v5
	s_waitcnt lgkmcnt(1)
	v_add_f32_e32 v1, v1, v3
	v_cndmask_b32_e32 v6, v0, v10, vcc
	v_lshlrev_b32_e32 v6, 2, v6
	s_waitcnt lgkmcnt(0)
	v_add_f32_e32 v3, v2, v4
	ds_bpermute_b32 v2, v6, v1
	ds_bpermute_b32 v4, v6, v3
	v_cmp_lt_i32_e32 vcc, v11, v5
	s_waitcnt lgkmcnt(1)
	v_add_f32_e32 v2, v1, v2
	v_cndmask_b32_e32 v0, v0, v11, vcc
	v_lshlrev_b32_e32 v5, 2, v0
	s_waitcnt lgkmcnt(0)
	v_add_f32_e32 v0, v3, v4
	ds_bpermute_b32 v3, v5, v2
	ds_bpermute_b32 v1, v5, v0
	s_cbranch_scc0 .LBB0_583
	s_waitcnt lgkmcnt(1)
	v_add_f32_e32 v2, v2, v3
	s_mov_b32 s1, 0x3fb8aa3b
	v_mul_f32_e32 v3, 0x3fb8aa3b, v2
	v_fma_f32 v4, v2, s1, -v3
	v_rndne_f32_e32 v5, v3
	v_fmac_f32_e32 v4, 0x32a5705f, v2
	v_sub_f32_e32 v3, v3, v5
	v_add_f32_e32 v3, v3, v4
	v_exp_f32_e32 v3, v3
	v_cvt_i32_f32_e32 v4, v5
	s_waitcnt lgkmcnt(0)
	v_add_f32_e32 v0, v0, v1
	s_mov_b32 s2, 0xc2ce8ed0
	v_cmp_ngt_f32_e32 vcc, s2, v2
	v_ldexp_f32 v1, v3, v4
	v_mul_f32_e32 v3, 0x3fb8aa3b, v0
	v_fma_f32 v4, v0, s1, -v3
	v_rndne_f32_e32 v5, v3
	v_fmac_f32_e32 v4, 0x32a5705f, v0
	v_sub_f32_e32 v3, v3, v5
	v_add_f32_e32 v3, v3, v4
	v_exp_f32_e32 v3, v3
	v_cvt_i32_f32_e32 v4, v5
	s_mov_b32 s3, 0x42b17218
	v_cndmask_b32_e32 v1, 0, v1, vcc
	v_mov_b32_e32 v5, 0x7f800000
	v_cmp_nlt_f32_e32 vcc, s3, v2
	v_ldexp_f32 v2, v3, v4
	v_readlane_b32 s1, v254, 13
	v_cndmask_b32_e32 v1, v5, v1, vcc
	v_cmp_ngt_f32_e32 vcc, s2, v0
	s_add_u32 s1, s1, 0x1aa00000
	v_readlane_b32 s2, v254, 14
	v_cndmask_b32_e32 v2, 0, v2, vcc
	v_cmp_nlt_f32_e32 vcc, s3, v0
	v_readlane_b32 s3, v254, 7
	s_addc_u32 s2, s2, 0
	s_lshl_b32 s3, s3, 13
	s_add_i32 s3, s3, 0
	s_add_i32 s3, s3, 0x10000
	s_add_u32 s4, s94, s84
	s_load_dwordx2 s[10:11], s[6:7], 0x78
	s_addc_u32 s5, s95, s85
	v_cndmask_b32_e32 v0, v5, v2, vcc
	s_add_u32 s18, s4, 0xaa80400
	v_sub_f32_e32 v0, v1, v0
	s_addc_u32 s19, s5, 0
	v_add_f32_e32 v180, 0x3e4ccccd, v0
	s_add_u32 s20, s4, 0x12a00100
	v_mov_b32_e32 v181, v180
	s_addc_u32 s21, s5, 0
	v_mov_b32_e32 v183, 0
	s_movk_i32 s22, 0x7c0
	s_movk_i32 s23, 0x90
	s_movk_i32 s24, 0x8000
	s_mov_b32 s25, 0x40000
	s_mov_b32 s26, 0x41000000
	s_mov_b64 s[12:13], 0x40000
	s_mov_b64 s[14:15], 0x80
	v_mov_b32_e32 v210, 0x358637bd
	s_mov_b32 s27, 0xf800000
	v_mov_b32_e32 v211, 0x260
	s_mov_b32 s28, 0x3f4ccccd
	s_mov_b32 s4, s88
	s_branch .LBB0_567

; __device__ __forceinline__ int lane_now() { int l; asm volatile("v_mbcnt_lo_u32_b32 %0, -1, 0\n\tv_mbcnt_hi_u32_b32 %0, -1, %0" : "=v"(l)); return l; }
; __device__ __forceinline__ unsigned xb_ld(unsigned* p)              { return __hip_atomic_load(p, __ATOMIC_RELAXED, __HIP_MEMORY_SCOPE_AGENT); }
; __device__ __forceinline__ void xcd_barrier_complete(unsigned* bar, unsigned x, unsigned& nloc, unsigned& nx) {
;     const unsigned G = gridDim.x * gridDim.y * gridDim.z;
;     unsigned sum, cnt, mine, sp = 0u;
;     for (;;) {
;         sum = 0u; cnt = 0u; mine = 0u;
; #pragma unroll
;         for (unsigned j = 0; j < 16; ++j) { const unsigned c = xb_ld(&bar[XB_XCNT(j)]); sum += c; cnt += (c > 0u) ? 1u : 0u; mine = (j == x) ? c : mine; }
; __device__ __forceinline__ void xcd_barrier(const XcdBarrier& b) {
;     asm volatile("s_waitcnt vmcnt(0)" ::: "memory");
;     __syncthreads();
;     if (b.wave == 0 && lane_now() == 0) {
;         unsigned* bar = b.bar;
;         __builtin_amdgcn_s_waitcnt(0);
;         unsigned nloc = b.st[0], nx = b.st[1];
;         if (nloc == 0u) { xcd_barrier_complete(bar, b.x, nloc, nx); b.st[0] = nloc; b.st[1] = nx; }
.LBB0_638:
	s_setprio 0
	s_waitcnt lgkmcnt(0)
	s_cmp_gt_i32 s93, 5
	s_cselect_b64 s[6:7], -1, 0
	s_and_b64 s[0:1], s[38:39], s[6:7]
	s_andn2_b64 vcc, exec, s[0:1]
	s_cbranch_vccnz .LBB0_694
	s_waitcnt vmcnt(0)
	v_readlane_b32 s0, v254, 9
	v_readlane_b32 s1, v254, 10
	s_and_b64 vcc, exec, s[0:1]
	s_waitcnt vmcnt(0)
	s_barrier
	s_cbranch_vccnz .LBB0_693
	v_mbcnt_lo_u32_b32 v0, -1, 0
	v_mbcnt_hi_u32_b32 v0, -1, v0
	s_nop 0
	v_cmp_eq_u32_e32 vcc, 0, v0
	s_and_saveexec_b64 s[8:9], vcc
	s_cbranch_execz .LBB0_692
	s_add_i32 s0, 0, 0x20000
	v_mov_b32_e32 v0, s0
	s_waitcnt vmcnt(0) expcnt(0) lgkmcnt(0)
	ds_read_b32 v2, v0
	s_add_i32 s0, 0, 0x20004
	v_mov_b32_e32 v0, s0
	ds_read_b32 v0, v0
	s_waitcnt lgkmcnt(1)
	v_cmp_ne_u32_e32 vcc, 0, v2
	s_cbranch_vccnz .LBB0_656
	s_add_u32 s10, s94, 0x1c0200
	s_addc_u32 s11, s95, 0
	s_add_u32 s12, s94, 0x1c0400
	s_addc_u32 s13, s95, 0
	s_add_u32 s14, s94, 0x1c0500
	s_addc_u32 s15, s95, 0
	s_add_u32 s16, s94, 0x1c0600
	s_addc_u32 s17, s95, 0
	s_add_u32 s18, s94, 0x1c0700
	s_addc_u32 s19, s95, 0
	s_add_u32 s20, s94, 0x1c0800
	s_addc_u32 s21, s95, 0
	s_add_u32 s22, s94, 0x1c0900
	s_addc_u32 s23, s95, 0
	s_add_u32 s24, s94, 0x1c0a00
	s_addc_u32 s25, s95, 0
	s_add_u32 s26, s94, 0x1c0b00
	s_addc_u32 s27, s95, 0
	s_add_u32 s28, s94, 0x1c0c00
	s_addc_u32 s29, s95, 0
	s_add_u32 s30, s94, 0x1c0d00
	s_addc_u32 s31, s95, 0
	s_add_u32 s34, s94, 0x1c0e00
	s_addc_u32 s35, s95, 0
	s_add_u32 s36, s94, 0x1c0f00
	v_readlane_b32 s0, v254, 5
	s_addc_u32 s37, s95, 0
	v_readlane_b32 s1, v254, 6
	s_add_u32 s38, s94, 0x1c1000
	s_load_dword s0, s[0:1], 0x120
	s_addc_u32 s39, s95, 0
	s_add_u32 s40, s94, 0x1c1100
	s_addc_u32 s41, s95, 0
	s_add_u32 s42, s94, 0x1c1200
	s_addc_u32 s43, s95, 0
	s_waitcnt lgkmcnt(0)
	s_mul_i32 s0, s81, s0
	s_add_u32 s44, s94, 0x1c1300
	s_mul_i32 s0, s0, s80
	s_addc_u32 s45, s95, 0
	s_mov_b32 s1, 1
	v_mov_b32_e32 v16, 0
	s_branch .LBB0_644

; __global__ void __launch_bounds__(512, 2) fwd_kernel(Params P) {
;     ...
;                     { const bf16_t* Q1 = (const bf16_t*)(ws + WS_Q1); const bf16_t* K1 = (const bf16_t*)(ws + WS_K1); const bf16_t* VT = (const bf16_t*)(ws + WS_VT1);
;                       for (int rep = 0; rep < REP_ATT; ++rep) for (int r = 0;; ++r) { const int u = SNAKE(r); if (u >= 2048) break;
;                           const int qb = 15 - (u >> 7), bh = u & 127, b = bh >> 4, h = bh & 15;
;                           attn_unit<96, 64, 0, 3, false>(lds, Q1 + (size_t)b * SEQ * 1536 + h * 96, 1536, K1 + (size_t)b * SEQ * 1536 + h * 96, 1536,
;                                                VT + (size_t)(h * 64) * MTOK + (size_t)b * SEQ, MTOK, (bf16_t*)(ws + WS_O1) + (size_t)b * SEQ * 1024 + h * 64, 1024,
;                                                qb * 256, qb * 4 + 4, 0.10206207261596575f * LOG2E, IN(22), nullptr, 0.f, 0.f, wave_s); } }
.LBB0_1633:
	v_readlane_b32 s0, v254, 8
	s_cmp_lt_i32 s0, 16
	s_cselect_b64 s[12:13], -1, 0
	s_and_b64 s[0:1], s[12:13], s[6:7]
	s_andn2_b64 vcc, exec, s[0:1]
	s_cbranch_vccnz .LBB0_1727
	s_cmpk_gt_i32 s88, 0x7ff
	v_mbcnt_lo_u32_b32 v0, -1, 0
	v_mbcnt_hi_u32_b32 v0, -1, v0
	s_mov_b32 s14, 0
	s_cbranch_scc1 .LBB0_1727
	v_readlane_b32 s98, v254, 7
	s_nop 3
	s_cmp_lt_u32 s98, 4
	s_cbranch_scc1 .Lk16_prio_mla
	s_setprio 1
.Lk16_prio_mla:
	s_ashr_i32 s15, s14, 31
	s_add_u32 s2, s94, s14
	s_addc_u32 s4, s95, s15
	s_add_u32 s0, s2, 0xea00000
	s_addc_u32 s1, s4, 0
	s_add_u32 s3, s2, 0x14a00000
	s_addc_u32 s28, s4, 0
	s_add_u32 s29, s2, 0x1aa00000
	s_addc_u32 s30, s4, 0
	s_not_b32 s5, s88
	s_add_i32 s31, s80, s5
	s_add_u32 s33, s2, 0xaa00000
	v_readlane_b32 s2, v254, 0
	s_addc_u32 s34, s4, 0
	s_and_b32 s35, s2, 0xffffffc0
	v_readlane_b32 s2, v254, 7
	s_lshl_b32 s36, s2, 5
	s_lshl_b64 s[4:5], s[14:15], 3
	v_readlane_b32 s6, v254, 5
	v_readlane_b32 s7, v254, 6
	s_add_u32 s4, s6, s4
	s_addc_u32 s5, s7, s5
	s_load_dwordx2 s[16:17], s[4:5], 0xb0
	s_add_u32 s37, s94, 0x1aa00300
	s_addc_u32 s38, s95, 0
	s_mov_b32 s43, 0
	s_movk_i32 s39, 0xc00
	v_mov_b32_e32 v169, 0
	s_mov_b32 s40, 0x2aaaaaab
	s_movk_i32 s41, 0x600
	s_movk_i32 s42, 0x300
	s_movk_i32 s44, 0xff
	s_movk_i32 s45, 0x100
	s_movk_i32 s46, 0xd0
	s_movk_i32 s47, 0x90
	v_mov_b32_e32 v180, 0x358637bd
	s_mov_b32 s48, 0xf800000
	v_mov_b32_e32 v181, 0x260
	s_add_i32 s49, 0, 0x10800
	s_add_i32 s50, 0, 0x13c00
	s_mov_b32 s51, 0x41000000
	s_mov_b64 s[18:19], 0xc0000
	s_mov_b64 s[20:21], 0x200
	s_mov_b32 s2, s88
	s_branch .LBB0_1637

; __device__ __forceinline__ int lane_now() { int l; asm volatile("v_mbcnt_lo_u32_b32 %0, -1, 0\n\tv_mbcnt_hi_u32_b32 %0, -1, %0" : "=v"(l)); return l; }
; __device__ __forceinline__ unsigned xb_ld(unsigned* p)              { return __hip_atomic_load(p, __ATOMIC_RELAXED, __HIP_MEMORY_SCOPE_AGENT); }
; __device__ __forceinline__ void xcd_barrier_complete(unsigned* bar, unsigned x, unsigned& nloc, unsigned& nx) {
;     const unsigned G = gridDim.x * gridDim.y * gridDim.z;
;     unsigned sum, cnt, mine, sp = 0u;
;     for (;;) {
;         sum = 0u; cnt = 0u; mine = 0u;
; #pragma unroll
;         for (unsigned j = 0; j < 16; ++j) { const unsigned c = xb_ld(&bar[XB_XCNT(j)]); sum += c; cnt += (c > 0u) ? 1u : 0u; mine = (j == x) ? c : mine; }
; __device__ __forceinline__ void xcd_barrier(const XcdBarrier& b) {
;     asm volatile("s_waitcnt vmcnt(0)" ::: "memory");
;     __syncthreads();
;     if (b.wave == 0 && lane_now() == 0) {
;         unsigned* bar = b.bar;
;         __builtin_amdgcn_s_waitcnt(0);
;         unsigned nloc = b.st[0], nx = b.st[1];
;         if (nloc == 0u) { xcd_barrier_complete(bar, b.x, nloc, nx); b.st[0] = nloc; b.st[1] = nx; }
.LBB0_1727:
	s_setprio 0
	s_cmp_gt_i32 s93, 16
	s_cselect_b64 s[6:7], -1, 0
	s_and_b64 s[0:1], s[12:13], s[6:7]
	s_andn2_b64 vcc, exec, s[0:1]
	s_cbranch_vccnz .LBB0_1783
	s_waitcnt vmcnt(0)
	v_readlane_b32 s0, v254, 9
	v_readlane_b32 s1, v254, 10
	s_and_b64 vcc, exec, s[0:1]
	s_waitcnt vmcnt(0) lgkmcnt(0)
	s_barrier
	s_cbranch_vccnz .LBB0_1782
	v_mbcnt_lo_u32_b32 v0, -1, 0
	v_mbcnt_hi_u32_b32 v0, -1, v0
	s_nop 0
	v_cmp_eq_u32_e32 vcc, 0, v0
	s_and_saveexec_b64 s[8:9], vcc
	s_cbranch_execz .LBB0_1781
	s_add_i32 s0, 0, 0x20000
	v_mov_b32_e32 v0, s0
	s_waitcnt vmcnt(0) expcnt(0) lgkmcnt(0)
	ds_read_b32 v2, v0
	s_add_i32 s0, 0, 0x20004
	v_mov_b32_e32 v0, s0
	ds_read_b32 v0, v0
	s_waitcnt lgkmcnt(1)
	v_cmp_ne_u32_e32 vcc, 0, v2
	s_cbranch_vccnz .LBB0_1745
	s_add_u32 s10, s94, 0x1c0200
	s_addc_u32 s11, s95, 0
	s_add_u32 s12, s94, 0x1c0400
	s_addc_u32 s13, s95, 0
	s_add_u32 s14, s94, 0x1c0500
	s_addc_u32 s15, s95, 0
	s_add_u32 s16, s94, 0x1c0600
	s_addc_u32 s17, s95, 0
	s_add_u32 s18, s94, 0x1c0700
	s_addc_u32 s19, s95, 0
	s_add_u32 s20, s94, 0x1c0800
	s_addc_u32 s21, s95, 0
	s_add_u32 s22, s94, 0x1c0900
	s_addc_u32 s23, s95, 0
	s_add_u32 s24, s94, 0x1c0a00
	s_addc_u32 s25, s95, 0
	s_add_u32 s26, s94, 0x1c0b00
	s_addc_u32 s27, s95, 0
	s_add_u32 s28, s94, 0x1c0c00
	s_addc_u32 s29, s95, 0
	s_add_u32 s30, s94, 0x1c0d00
	s_addc_u32 s31, s95, 0
	s_add_u32 s34, s94, 0x1c0e00
	s_addc_u32 s35, s95, 0
	s_add_u32 s36, s94, 0x1c0f00
	v_readlane_b32 s0, v254, 5
	s_addc_u32 s37, s95, 0
	v_readlane_b32 s1, v254, 6
	s_add_u32 s38, s94, 0x1c1000
	s_load_dword s0, s[0:1], 0x120
	s_addc_u32 s39, s95, 0
	s_add_u32 s40, s94, 0x1c1100
	s_addc_u32 s41, s95, 0
	s_add_u32 s42, s94, 0x1c1200
	s_addc_u32 s43, s95, 0
	s_waitcnt lgkmcnt(0)
	s_mul_i32 s0, s81, s0
	s_add_u32 s44, s94, 0x1c1300
	s_mul_i32 s0, s0, s80
	s_addc_u32 s45, s95, 0
	s_mov_b32 s1, 1
	v_mov_b32_e32 v16, 0
	s_branch .LBB0_1733
